# grid barriers 1-4: the first workgroup of each XCD to arrive issues one early buffer_wbl2 so the last arriver's writeback has less to flush
# baseline (speedup 1.0000x reference)
.LBB0_189:
	s_or_b64 exec, exec, s[28:29]
	v_cvt_f32_u32_e32 v4, v2
	s_waitcnt vmcnt(0)
	v_readfirstlane_b32 s3, v3
	v_sub_u32_e32 v3, 0, v2
	v_rcp_iflag_f32_e32 v4, v4
	v_add_u32_e32 v5, s3, v1
	v_mul_f32_e32 v4, 0x4f7ffffe, v4
	v_cvt_u32_f32_e32 v4, v4
	v_mul_lo_u32 v1, v3, v4
	v_mul_hi_u32 v1, v4, v1
	v_add_u32_e32 v1, v4, v1
	v_mul_hi_u32 v1, v5, v1
	v_mul_lo_u32 v3, v1, v2
	v_sub_u32_e32 v3, v5, v3
	v_add_u32_e32 v4, 1, v1
	v_cmp_ge_u32_e32 vcc, v3, v2
	s_nop 1
	v_cndmask_b32_e32 v1, v1, v4, vcc
	v_sub_u32_e32 v4, v3, v2
	v_cndmask_b32_e32 v3, v3, v4, vcc
	v_add_u32_e32 v4, 1, v1
	v_cmp_ge_u32_e32 vcc, v3, v2
	v_add_u32_e32 v3, 1, v5
	s_nop 0
	v_cndmask_b32_e32 v1, v1, v4, vcc
	v_mul_lo_u32 v4, v2, v1
	v_add_u32_e32 v2, v4, v2
	v_cmp_ne_u32_e32 vcc, v3, v2
	s_and_saveexec_b64 s[10:11], vcc
	s_xor_b64 s[10:11], exec, s[10:11]
	s_cbranch_execz .LBB0_203
	s_waitcnt lgkmcnt(0)
	v_cmp_eq_u32_e32 vcc, v5, v4
	s_cbranch_vccz .Lewb_0
	buffer_wbl2 sc1
.Lewb_0:
	v_mov_b32_e32 v0, 0
	s_add_u32 s58, s56, 0x13dad500
	s_addc_u32 s59, s57, 0
	global_load_dword v0, v0, s[58:59] sc1
	s_waitcnt vmcnt(0)
	v_cmp_eq_u32_e32 vcc, v0, v1
	s_and_saveexec_b64 s[28:29], vcc
	s_cbranch_execz .LBB0_202
	s_add_u32 s34, s56, 0x13daa200
	s_addc_u32 s35, s57, 0
	s_mov_b32 s3, 1
	s_mov_b64 s[60:61], 0
	v_mov_b32_e32 v0, 0
	s_branch .LBB0_193

.LBB0_382:
	s_or_b64 exec, exec, s[10:11]
	v_cvt_f32_u32_e32 v4, v2
	s_waitcnt vmcnt(0)
	v_readfirstlane_b32 s3, v3
	v_sub_u32_e32 v3, 0, v2
	v_rcp_iflag_f32_e32 v4, v4
	v_add_u32_e32 v5, s3, v1
	v_mul_f32_e32 v4, 0x4f7ffffe, v4
	v_cvt_u32_f32_e32 v4, v4
	v_mul_lo_u32 v1, v3, v4
	v_mul_hi_u32 v1, v4, v1
	v_add_u32_e32 v1, v4, v1
	v_mul_hi_u32 v1, v5, v1
	v_mul_lo_u32 v3, v1, v2
	v_sub_u32_e32 v3, v5, v3
	v_add_u32_e32 v4, 1, v1
	v_cmp_ge_u32_e32 vcc, v3, v2
	s_nop 1
	v_cndmask_b32_e32 v1, v1, v4, vcc
	v_sub_u32_e32 v4, v3, v2
	v_cndmask_b32_e32 v3, v3, v4, vcc
	v_add_u32_e32 v4, 1, v1
	v_cmp_ge_u32_e32 vcc, v3, v2
	v_add_u32_e32 v3, 1, v5
	s_nop 0
	v_cndmask_b32_e32 v1, v1, v4, vcc
	v_mul_lo_u32 v4, v2, v1
	v_add_u32_e32 v2, v4, v2
	v_cmp_ne_u32_e32 vcc, v3, v2
	s_and_saveexec_b64 s[8:9], vcc
	s_xor_b64 s[8:9], exec, s[8:9]
	s_cbranch_execz .LBB0_396
	s_waitcnt lgkmcnt(0)
	v_cmp_eq_u32_e32 vcc, v5, v4
	s_cbranch_vccz .Lewb_1
	buffer_wbl2 sc1
.Lewb_1:
	v_mov_b32_e32 v0, 0
	s_add_u32 s22, s56, 0x13dad500
	s_addc_u32 s23, s57, 0
	global_load_dword v0, v0, s[22:23] sc1
	s_waitcnt vmcnt(0)
	v_cmp_eq_u32_e32 vcc, v0, v1
	s_and_saveexec_b64 s[10:11], vcc
	s_cbranch_execz .LBB0_395
	s_add_u32 s20, s56, 0x13daa200
	s_addc_u32 s21, s57, 0
	s_mov_b32 s3, 1
	s_mov_b64 s[28:29], 0
	v_mov_b32_e32 v0, 0
	s_branch .LBB0_386

.LBB0_488:
	s_or_b64 exec, exec, s[16:17]
	v_cvt_f32_u32_e32 v4, v2
	s_waitcnt vmcnt(0)
	v_readfirstlane_b32 s3, v3
	v_sub_u32_e32 v3, 0, v2
	v_rcp_iflag_f32_e32 v4, v4
	v_add_u32_e32 v5, s3, v1
	v_mul_f32_e32 v4, 0x4f7ffffe, v4
	v_cvt_u32_f32_e32 v4, v4
	v_mul_lo_u32 v1, v3, v4
	v_mul_hi_u32 v1, v4, v1
	v_add_u32_e32 v1, v4, v1
	v_mul_hi_u32 v1, v5, v1
	v_mul_lo_u32 v3, v1, v2
	v_sub_u32_e32 v3, v5, v3
	v_add_u32_e32 v4, 1, v1
	v_cmp_ge_u32_e32 vcc, v3, v2
	s_nop 1
	v_cndmask_b32_e32 v1, v1, v4, vcc
	v_sub_u32_e32 v4, v3, v2
	v_cndmask_b32_e32 v3, v3, v4, vcc
	v_add_u32_e32 v4, 1, v1
	v_cmp_ge_u32_e32 vcc, v3, v2
	v_add_u32_e32 v3, 1, v5
	s_nop 0
	v_cndmask_b32_e32 v1, v1, v4, vcc
	v_mul_lo_u32 v4, v2, v1
	v_add_u32_e32 v2, v4, v2
	v_cmp_ne_u32_e32 vcc, v3, v2
	s_and_saveexec_b64 s[10:11], vcc
	s_xor_b64 s[10:11], exec, s[10:11]
	s_cbranch_execz .LBB0_502
	s_waitcnt lgkmcnt(0)
	v_cmp_eq_u32_e32 vcc, v5, v4
	s_cbranch_vccz .Lewb_2
	buffer_wbl2 sc1
.Lewb_2:
	v_mov_b32_e32 v0, 0
	s_add_u32 s20, s56, 0x13dad500
	s_addc_u32 s21, s57, 0
	global_load_dword v0, v0, s[20:21] sc1
	s_waitcnt vmcnt(0)
	v_cmp_eq_u32_e32 vcc, v0, v1
	s_and_saveexec_b64 s[16:17], vcc
	s_cbranch_execz .LBB0_501
	s_add_u32 s18, s56, 0x13daa200
	s_addc_u32 s19, s57, 0
	s_mov_b32 s3, 1
	s_mov_b64 s[22:23], 0
	v_mov_b32_e32 v0, 0
	s_branch .LBB0_492

.Lewb_3:
	v_mov_b32_e32 v0, 0
	s_add_u32 s18, s56, 0x13dad500
	s_addc_u32 s19, s57, 0
	global_load_dword v0, v0, s[18:19] sc1
	s_waitcnt vmcnt(0)
	v_cmp_eq_u32_e32 vcc, v0, v1
	s_and_saveexec_b64 s[10:11], vcc
	s_cbranch_execz .LBB0_613
	s_add_u32 s16, s56, 0x13daa200
	s_addc_u32 s17, s57, 0
	s_mov_b32 s3, 1
	s_mov_b64 s[20:21], 0
	v_mov_b32_e32 v0, 0
	s_branch .LBB0_604
